# norm_pass: pre/post norm gain loads hoisted out of the row loop (removes per-store vmcnt(0) drains)
# speedup vs baseline: 1.0189x; 1.0044x over previous
.LBB0_407:
	s_add_i32 s1, s38, 8
	s_and_b64 s[6:7], s[2:3], exec
	s_cselect_b32 s1, s1, 0x4000
	s_cmp_ge_i32 s38, s1
	s_cbranch_scc1 .LBB0_483
	s_ashr_i32 s43, s42, 31
	s_mov_b32 s11, s62
	s_lshl_b64 s[6:7], s[42:43], 26
	v_readlane_b32 s60, v233, 40
	v_readlane_b32 s61, v233, 41
	s_add_u32 s8, s60, s6
	s_addc_u32 s9, s61, s7
	s_lshl_b32 s10, s31, 3
	s_and_b64 s[2:3], s[2:3], exec
	v_readlane_b32 s34, v233, 60
	s_load_dwordx2 s[2:3], s[40:41], 0x10
	s_cselect_b32 s42, 1, s10
	s_cmp_lt_i32 s34, 0
	s_waitcnt lgkmcnt(0)
	s_cselect_b32 s9, s9, s5
	s_cselect_b32 s8, s8, s4
	s_cmp_gt_i32 s34, 0
	v_readlane_b32 s35, v233, 61
	s_cselect_b64 s[44:45], -1, 0
	s_add_i32 s64, s34, -1
	v_lshlrev_b32_e32 v1, 2, v207
	s_lshl_b64 s[46:47], s[64:65], 12
	s_lshl_b64 s[4:5], s[34:35], 12
	v_and_b32_e32 v0, 0xfc, v1
	s_add_u32 s2, s2, s4
	s_addc_u32 s3, s3, s5
	v_lshlrev_b32_e32 v168, 2, v0
	s_ashr_i32 s39, s38, 31
	v_lshl_add_u64 v[16:17], s[2:3], 0, v[168:169]
	s_lshl_b64 s[2:3], s[38:39], 11
	v_readlane_b32 s4, v233, 39
	s_add_u32 s4, s4, s48
	v_readlane_b32 s5, v233, 44
	s_addc_u32 s5, s5, 0
	v_bitop3_b32 v20, v1, 4, v200 bitop3:0x6c
	v_bitop3_b32 v21, v1, 8, v200 bitop3:0x6c
	v_bitop3_b32 v22, v1, 16, v200 bitop3:0x6c
	v_bitop3_b32 v23, v1, 32, v200 bitop3:0x6c
	v_bitop3_b32 v24, v1, 64, v200 bitop3:0x6c
	v_bitop3_b32 v25, v1, s14, v200 bitop3:0x6c
	v_and_b32_e32 v1, 63, v207
	s_add_u32 s2, s4, s2
	v_lshlrev_b32_e32 v168, 3, v1
	s_addc_u32 s3, s5, s3
	s_ashr_i32 s43, s42, 31
	v_lshl_add_u64 v[18:19], s[2:3], 0, v[168:169]
	s_lshl_b64 s[52:53], s[42:43], 11
	s_lshl_b64 s[2:3], s[38:39], 12
	s_add_u32 s54, s8, s2
	s_addc_u32 s55, s9, s3
	s_lshl_b64 s[56:57], s[42:43], 12
	s_add_u32 s2, s6, s2
	s_addc_u32 s3, s7, s3
	s_add_u32 s58, s60, s2
	v_lshlrev_b32_e32 v168, 4, v1
	s_addc_u32 s59, s61, s3
	v_lshlrev_b32_e32 v26, 2, v0
	v_readlane_b32 s62, v233, 42
	v_readlane_b32 s63, v233, 43
	global_load_dwordx4 v[76:79], v[16:17], off
	global_load_dwordx4 v[80:83], v[16:17], off offset:1024
	global_load_dwordx4 v[84:87], v[16:17], off offset:2048
	global_load_dwordx4 v[88:91], v[16:17], off offset:3072
	s_andn2_b64 vcc, exec, s[44:45]
	s_cbranch_vccnz .Lnp_noq
	s_load_dwordx2 s[2:3], s[40:41], 0x18
	s_waitcnt lgkmcnt(0)
	s_add_u32 s2, s2, s46
	s_addc_u32 s3, s3, s47
	global_load_dwordx4 v[60:63], v26, s[2:3]
	global_load_dwordx4 v[64:67], v26, s[2:3] offset:1024
	global_load_dwordx4 v[68:71], v26, s[2:3] offset:2048
	global_load_dwordx4 v[72:75], v26, s[2:3] offset:3072
.Lnp_noq:
	s_waitcnt vmcnt(0)
	s_branch .LBB0_410

.Lnp_409b:
	v_mul_f32_e32 v27, v13, v13
	v_mul_f32_e32 v42, v9, v9
	v_pk_mul_f32 v[36:37], v[0:1], v[0:1]
	v_pk_mul_f32 v[38:39], v[4:5], v[4:5]
	v_pk_mul_f32 v[32:33], v[2:3], v[2:3]
	v_pk_mul_f32 v[34:35], v[6:7], v[6:7]
	v_fmac_f32_e32 v27, v12, v12
	v_fmac_f32_e32 v42, v8, v8
	v_mov_b32_e32 v40, v36
	v_mov_b32_e32 v41, v38
	v_mov_b32_e32 v38, v37
	v_mov_b32_e32 v36, v32
	v_mov_b32_e32 v37, v34
	v_mov_b32_e32 v34, v33
	v_fmac_f32_e32 v27, v14, v14
	v_fmac_f32_e32 v42, v10, v10
	v_pk_add_f32 v[32:33], v[40:41], v[38:39]
	v_fmac_f32_e32 v27, v15, v15
	v_fmac_f32_e32 v42, v11, v11
	v_pk_add_f32 v[32:33], v[36:37], v[32:33]
	v_add_f32_e32 v27, v27, v42
	v_pk_add_f32 v[32:33], v[34:35], v[32:33]
	s_mov_b32 s2, 0xe5f00000
	v_add_f32_e32 v27, v33, v27
	v_add_f32_e32 v27, v32, v27
	s_nop 1
	v_mov_b32_dpp v32, v27 quad_perm:[1,0,3,2] row_mask:0xf bank_mask:0xf
	v_mov_b32_e32 v33, s0
	v_add_co_u32_e32 v34, vcc, s2, v18
	s_mov_b32 s2, 0xe5f01000
	s_waitcnt lgkmcnt(0)
	v_add_f32_e32 v27, v27, v32
	s_nop 1
	v_mov_b32_dpp v32, v27 quad_perm:[2,3,0,1] row_mask:0xf bank_mask:0xf
	v_addc_co_u32_e32 v35, vcc, -1, v19, vcc
	s_add_i32 s38, s38, s42
	s_add_u32 s54, s54, s56
	s_waitcnt lgkmcnt(0)
	v_add_f32_e32 v27, v27, v32
	s_nop 1
	v_mov_b32_dpp v32, v27 row_half_mirror row_mask:0xf bank_mask:0xf
	s_addc_u32 s55, s55, s57
	s_add_u32 s58, s58, s56
	s_addc_u32 s59, s59, s57
	s_cmp_ge_i32 s38, s1
	s_waitcnt lgkmcnt(0)
	v_add_f32_e32 v27, v27, v32
	s_nop 1
	v_mov_b32_dpp v32, v27 row_mirror row_mask:0xf bank_mask:0xf
	s_waitcnt lgkmcnt(0)
	v_add_f32_e32 v27, v27, v32
	v_mov_b32_e32 v32, v27
	s_nop 1
	v_permlane16_swap_b32_e32 v27, v32
	s_waitcnt lgkmcnt(0)
	v_add_f32_e32 v27, v27, v32
	v_mov_b32_e32 v32, v27
	s_nop 1
	v_permlane32_swap_b32_e32 v27, v32
	s_waitcnt lgkmcnt(0)
	v_add_f32_e32 v27, v27, v32
	v_fmamk_f32 v27, v27, 0x3a800000, v33
	v_rsq_f32_e32 v32, v27
	s_nop 0
	v_pk_mul_f32 v[12:13], v[12:13], v[32:33] op_sel_hi:[1,0]
	v_pk_mul_f32 v[14:15], v[14:15], v[32:33] op_sel_hi:[1,0]
	v_pk_mul_f32 v[8:9], v[8:9], v[32:33] op_sel_hi:[1,0]
	v_pk_mul_f32 v[10:11], v[10:11], v[32:33] op_sel_hi:[1,0]
	v_pk_mul_f32 v[4:5], v[4:5], v[32:33] op_sel_hi:[1,0]
	v_pk_mul_f32 v[6:7], v[6:7], v[32:33] op_sel_hi:[1,0]
	v_pk_mul_f32 v[0:1], v[0:1], v[32:33] op_sel_hi:[1,0]
	v_pk_mul_f32 v[2:3], v[2:3], v[32:33] op_sel_hi:[1,0]
	v_pk_mul_f32 v[12:13], v[76:77], v[12:13]
	v_pk_mul_f32 v[14:15], v[78:79], v[14:15]
	v_cvt_pk_bf16_f32 v12, v12, v13
	v_add_co_u32_e32 v28, vcc, s2, v18
	v_cvt_pk_bf16_f32 v13, v14, v15
	global_store_dwordx2 v[34:35], v[12:13], off
	v_addc_co_u32_e32 v29, vcc, -1, v19, vcc
	v_lshl_add_u64 v[18:19], v[18:19], 0, s[52:53]
	v_pk_mul_f32 v[8:9], v[80:81], v[8:9]
	v_pk_mul_f32 v[10:11], v[82:83], v[10:11]
	v_cvt_pk_bf16_f32 v8, v8, v9
	s_nop 0
	v_cvt_pk_bf16_f32 v9, v10, v11
	global_store_dwordx2 v[28:29], v[8:9], off offset:-3584
	v_pk_mul_f32 v[4:5], v[84:85], v[4:5]
	v_pk_mul_f32 v[6:7], v[86:87], v[6:7]
	v_cvt_pk_bf16_f32 v4, v4, v5
	s_nop 0
	v_cvt_pk_bf16_f32 v5, v6, v7
	global_store_dwordx2 v[28:29], v[4:5], off offset:-3072
	v_pk_mul_f32 v[0:1], v[0:1], v[88:89]
	v_pk_mul_f32 v[2:3], v[2:3], v[90:91]
	v_cvt_pk_bf16_f32 v0, v0, v1
	s_nop 0
	v_cvt_pk_bf16_f32 v1, v2, v3
	global_store_dwordx2 v[28:29], v[0:1], off offset:-2560
	s_cbranch_scc1 .LBB0_412
.LBB0_410:
	v_lshl_add_u64 v[0:1], s[54:55], 0, v[168:169]
	global_load_dwordx4 v[12:15], v[0:1], off
	global_load_dwordx4 v[8:11], v[0:1], off offset:1024
	global_load_dwordx4 v[4:7], v[0:1], off offset:2048
	s_nop 0
	global_load_dwordx4 v[0:3], v[0:1], off offset:3072
	s_andn2_b64 vcc, exec, s[44:45]
	s_cbranch_vccnz .LBB0_409
	global_load_dwordx2 v[32:33], v[18:19], off
	global_load_dwordx2 v[34:35], v[18:19], off offset:512
	global_load_dwordx2 v[36:37], v[18:19], off offset:1536
	global_load_dwordx2 v[38:39], v[18:19], off offset:1024
	s_load_dwordx2 s[2:3], s[40:41], 0x18
	s_waitcnt lgkmcnt(0)
	s_add_u32 s2, s2, s46
	s_addc_u32 s3, s3, s47
	s_waitcnt vmcnt(3)
	v_and_b32_e32 v41, 0xffff0000, v32
	s_waitcnt vmcnt(2)
	v_and_b32_e32 v43, 0xffff0000, v34
	v_lshlrev_b32_e32 v40, 16, v32
	v_lshlrev_b32_e32 v42, 16, v34
	s_waitcnt vmcnt(1)
	v_and_b32_e32 v47, 0xffff0000, v36
	s_waitcnt vmcnt(0)
	v_and_b32_e32 v46, 0xffff0000, v38
	v_mul_f32_e32 v27, v41, v41
	v_mul_f32_e32 v50, v43, v43
	v_lshlrev_b32_e32 v32, 16, v33
	v_lshlrev_b32_e32 v34, 16, v35
	v_lshlrev_b32_e32 v45, 16, v36
	v_lshlrev_b32_e32 v44, 16, v38
	v_lshlrev_b32_e32 v48, 16, v39
	v_and_b32_e32 v36, 0xffff0000, v39
	v_pk_mul_f32 v[38:39], v[46:47], v[46:47]
	v_fmac_f32_e32 v27, v40, v40
	v_fmac_f32_e32 v50, v42, v42
	v_and_b32_e32 v33, 0xffff0000, v33
	v_and_b32_e32 v35, 0xffff0000, v35
	v_lshlrev_b32_e32 v49, 16, v37
	v_pk_fma_f32 v[38:39], v[44:45], v[44:45], v[38:39]
	v_fmac_f32_e32 v27, v32, v32
	v_fmac_f32_e32 v50, v34, v34
	v_and_b32_e32 v37, 0xffff0000, v37
	v_pk_fma_f32 v[38:39], v[48:49], v[48:49], v[38:39]
	v_fmac_f32_e32 v27, v33, v33
	v_fmac_f32_e32 v50, v35, v35
	v_pk_fma_f32 v[38:39], v[36:37], v[36:37], v[38:39]
	v_add_f32_e32 v27, v27, v50
	v_add_f32_e32 v27, v27, v38
	v_add_f32_e32 v27, v27, v39
	s_nop 1
	v_mov_b32_dpp v38, v27 quad_perm:[1,0,3,2] row_mask:0xf bank_mask:0xf
	v_mov_b32_e32 v39, s0
	v_lshl_add_u64 v[50:51], s[58:59], 0, v[168:169]
	s_waitcnt lgkmcnt(0)
	v_add_f32_e32 v27, v27, v38
	s_nop 1
	v_mov_b32_dpp v38, v27 quad_perm:[2,3,0,1] row_mask:0xf bank_mask:0xf
	s_waitcnt lgkmcnt(0)
	v_add_f32_e32 v27, v27, v38
	s_nop 1
	v_mov_b32_dpp v38, v27 row_half_mirror row_mask:0xf bank_mask:0xf
	s_waitcnt lgkmcnt(0)
	v_add_f32_e32 v27, v27, v38
	s_nop 1
	v_mov_b32_dpp v38, v27 row_mirror row_mask:0xf bank_mask:0xf
	s_waitcnt lgkmcnt(0)
	v_add_f32_e32 v27, v27, v38
	v_mov_b32_e32 v38, v27
	s_nop 1
	v_permlane16_swap_b32_e32 v27, v38
	s_waitcnt lgkmcnt(0)
	v_add_f32_e32 v27, v27, v38
	v_mov_b32_e32 v38, v27
	s_nop 1
	v_permlane32_swap_b32_e32 v27, v38
	s_waitcnt lgkmcnt(0)
	v_add_f32_e32 v27, v27, v38
	v_fmamk_f32 v27, v27, 0x3a800000, v39
	v_rsq_f32_e32 v38, v27
	s_nop 0
	v_pk_mul_f32 v[40:41], v[40:41], v[38:39] op_sel_hi:[1,0]
	v_pk_mul_f32 v[32:33], v[32:33], v[38:39] op_sel_hi:[1,0]
	v_pk_fma_f32 v[12:13], v[60:61], v[40:41], v[12:13]
	v_pk_fma_f32 v[14:15], v[62:63], v[32:33], v[14:15]
	global_store_dwordx4 v[50:51], v[12:15], off
	v_pk_mul_f32 v[32:33], v[42:43], v[38:39] op_sel_hi:[1,0]
	v_pk_mul_f32 v[34:35], v[34:35], v[38:39] op_sel_hi:[1,0]
	v_pk_fma_f32 v[8:9], v[64:65], v[32:33], v[8:9]
	v_pk_fma_f32 v[10:11], v[66:67], v[34:35], v[10:11]
	global_store_dwordx4 v[50:51], v[8:11], off offset:1024
	v_mov_b32_e32 v32, v44
	v_mov_b32_e32 v33, v46
	v_mov_b32_e32 v34, v48
	v_mov_b32_e32 v35, v36
	v_pk_mul_f32 v[32:33], v[32:33], v[38:39] op_sel_hi:[1,0]
	v_pk_mul_f32 v[34:35], v[34:35], v[38:39] op_sel_hi:[1,0]
	v_mov_b32_e32 v46, v45
	v_mov_b32_e32 v36, v49
	v_pk_fma_f32 v[6:7], v[70:71], v[34:35], v[6:7]
	v_pk_fma_f32 v[4:5], v[68:69], v[32:33], v[4:5]
	global_store_dwordx4 v[50:51], v[4:7], off offset:2048
	v_pk_mul_f32 v[32:33], v[46:47], v[38:39] op_sel_hi:[1,0]
	v_pk_mul_f32 v[34:35], v[36:37], v[38:39] op_sel_hi:[1,0]
	v_pk_fma_f32 v[0:1], v[72:73], v[32:33], v[0:1]
	v_pk_fma_f32 v[2:3], v[74:75], v[34:35], v[2:3]
	global_store_dwordx4 v[50:51], v[0:3], off offset:3072
	s_branch .Lnp_409b
